# attention loop: score accumulators are re-initialised behind the PV MFMAs of the previous K tile (and once before the loop), so the segment after the barrier starts with LDS reads and MFMAs instead of
# baseline (speedup 1.0000x reference)
; __device__ void attn_phase(const Params& p, bool last, char* shm, int w0) {
;     ...
;     auto lstore = [&](int buf) {
;       *(u32x4*)(Ks + buf * 64 * KSTR + lk0) = rk0;
;       if (tid < 256) *(u32x4*)(Ks + buf * 64 * KSTR + lk1) = rk1;
;       *(u32x4*)(Vs + buf * 64 * VSTR + lv) = rv;
;     };
;     const int ntile = nkeys / 64;
;     __syncthreads();
;     gload(0); lstore(0);
;     __syncthreads();
;     for (int kt = 0; kt < ntile; ++kt) {
;       const int buf = kt & 1;
;       if (kt + 1 < ntile) gload(kt + 1);
;       if (act) {
;         const bf16_t* Kb = Ks + buf * 64 * KSTR; const bf16_t* Vb = Vs + buf * 64 * VSTR;
; #pragma unroll
;         for (int k2 = 0; k2 < 2; ++k2) {
;           f32x16 st[2];
; #pragma unroll
;           for (int j = 0; j < 2; ++j)
; #pragma unroll
;             for (int e = 0; e < 16; ++e) st[j][e] = -mrun[j];
.LBB0_645:
	s_or_b64 exec, exec, s[12:13]
	s_waitcnt vmcnt(1)
	ds_write_b128 v203, v[112:115] offset:13312
	s_and_saveexec_b64 s[12:13], s[6:7]
	ds_write_b128 v235, v[176:179] offset:13440
	s_or_b64 exec, exec, s[12:13]
	v_lshl_add_u64 v[14:15], v[206:207], 0, s[10:11]
	s_add_u32 s10, s15, s18
	s_addc_u32 s11, s14, 0
	v_lshl_add_u64 v[220:221], v[208:209], 0, s[10:11]
	v_lshl_add_u64 v[222:223], v[210:211], 0, s[0:1]
	s_mov_b32 s10, 0
	s_waitcnt vmcnt(0)
	ds_write_b128 v236, v[116:119] offset:35840
	s_waitcnt lgkmcnt(0)
	s_barrier
	v_xor_b32_e32 v224, 0x80000000, v217
	v_xor_b32_e32 v225, 0x80000000, v219
	v_mov_b32_e32 v96, v224
	v_mov_b32_e32 v97, v224
	v_mov_b32_e32 v98, v224
	v_mov_b32_e32 v99, v224
	v_mov_b32_e32 v100, v224
	v_mov_b32_e32 v101, v224
	v_mov_b32_e32 v102, v224
	v_mov_b32_e32 v103, v224
	v_mov_b32_e32 v104, v224
	v_mov_b32_e32 v105, v224
	v_mov_b32_e32 v106, v224
	v_mov_b32_e32 v107, v224
	v_mov_b32_e32 v108, v224
	v_mov_b32_e32 v109, v224
	v_mov_b32_e32 v110, v224
	v_mov_b32_e32 v111, v224
	v_mov_b32_e32 v112, v225
	v_mov_b32_e32 v113, v225
	v_mov_b32_e32 v114, v225
	v_mov_b32_e32 v115, v225
	v_mov_b32_e32 v116, v225
	v_mov_b32_e32 v117, v225
	v_mov_b32_e32 v118, v225
	v_mov_b32_e32 v119, v225
	v_mov_b32_e32 v120, v225
	v_mov_b32_e32 v121, v225
	v_mov_b32_e32 v122, v225
	v_mov_b32_e32 v123, v225
	v_mov_b32_e32 v124, v225
	v_mov_b32_e32 v125, v225
	v_mov_b32_e32 v126, v225
	v_mov_b32_e32 v127, v225
	s_branch .LBB0_649

; __device__ void attn_phase(const Params& p, bool last, char* shm, int w0) {
;     ...
;     for (int kt = 0; kt < ntile; ++kt) {
;       const int buf = kt & 1;
;       if (kt + 1 < ntile) gload(kt + 1);
;       if (act) {
;         const bf16_t* Kb = Ks + buf * 64 * KSTR; const bf16_t* Vb = Vs + buf * 64 * VSTR;
; #pragma unroll
;         for (int k2 = 0; k2 < 2; ++k2) {
;           f32x16 st[2];
; #pragma unroll
;           for (int j = 0; j < 2; ++j)
; #pragma unroll
;             for (int e = 0; e < 16; ++e) st[j][e] = -mrun[j];
; #pragma unroll
;           for (int ks = 0; ks < 6; ++ks) {
;             const bf16x8 kf = *(const bf16x8*)(Kb + (k2 * 32 + lq) * KSTR + ks * 16 + hb * 8);
;             st[0] = __builtin_amdgcn_mfma_f32_32x32x16_bf16(kf, qf[0][ks], st[0], 0, 0, 0);
;             st[1] = __builtin_amdgcn_mfma_f32_32x32x16_bf16(kf, qf[1][ks], st[1], 0, 0, 0);
;           }
;           bf16x8 pf[2][2];
; #pragma unroll
;           for (int qt = 0; qt < 2; ++qt) {
;             float mx = st[qt][0];
; #pragma unroll
;             for (int e = 1; e < 16; ++e) mx = fmaxf(mx, st[qt][e]);
;             mx = fmaxf(mx, __shfl_xor(mx, 32));
;             const bool first = (kt == 0 && k2 == 0);
;             if (first || __builtin_amdgcn_ballot_w64(mx > 6.f) != 0ull) {
.LBB0_651:
	s_or_b64 exec, exec, s[0:1]
	global_load_dwordx4 v[6:9], v[220:221], off
	s_add_i32 s10, s10, 1
	s_and_b32 s11, s10, 1
	s_and_saveexec_b64 s[0:1], s[8:9]
	s_cbranch_execz .LBB0_661
	s_mul_i32 s12, s11, 0x3400
	v_add_u32_e32 v0, s12, v237
	v_add_u32_e32 v215, v0, v240
	s_mul_i32 s12, s11, 0x2400
	ds_read_b128 v[180:183], v215 offset:0
	ds_read_b128 v[184:187], v215 offset:32
	ds_read_b128 v[188:191], v215 offset:64
	ds_read_b128 v[228:231], v215 offset:96
	ds_read_b128 v[80:83], v215 offset:128
	ds_read_b128 v[84:87], v215 offset:160
	v_add_u32_e32 v0, s12, v238
	v_add_u32_e32 v218, v0, v241
	v_add_u32_e32 v233, v0, v239
	v_add_u32_e32 v218, 0x6800, v218
	v_add_u32_e32 v233, 0x6800, v233
	ds_read2_b64 v[88:91], v218 offset1:2
	ds_read2_b64 v[242:245], v233 offset1:2
	ds_read2_b64 v[92:95], v218 offset0:4 offset1:6
	ds_read2_b64 v[246:249], v233 offset0:4 offset1:6
	s_waitcnt lgkmcnt(9)
	v_mfma_f32_32x32x16_bf16 v[96:111], v[180:183], v[128:131], v[96:111]
	s_waitcnt lgkmcnt(8)
	v_mfma_f32_32x32x16_bf16 v[96:111], v[184:187], v[132:135], v[96:111]
	s_waitcnt lgkmcnt(7)
	v_mfma_f32_32x32x16_bf16 v[96:111], v[188:191], v[136:139], v[96:111]
	s_waitcnt lgkmcnt(6)
	v_mfma_f32_32x32x16_bf16 v[96:111], v[228:231], v[140:143], v[96:111]
	s_waitcnt lgkmcnt(5)
	v_mfma_f32_32x32x16_bf16 v[96:111], v[80:83], v[144:147], v[96:111]
	s_waitcnt lgkmcnt(4)
	v_mfma_f32_32x32x16_bf16 v[96:111], v[84:87], v[148:151], v[96:111]
	v_mfma_f32_32x32x16_bf16 v[112:127], v[180:183], v[152:155], v[112:127]
	ds_read_b128 v[180:183], v215 offset:6656
	v_mfma_f32_32x32x16_bf16 v[112:127], v[184:187], v[156:159], v[112:127]
	ds_read_b128 v[184:187], v215 offset:6688
	v_mfma_f32_32x32x16_bf16 v[112:127], v[188:191], v[160:163], v[112:127]
	ds_read_b128 v[188:191], v215 offset:6720
	v_mfma_f32_32x32x16_bf16 v[112:127], v[228:231], v[164:167], v[112:127]
	ds_read_b128 v[228:231], v215 offset:6752
	v_mfma_f32_32x32x16_bf16 v[112:127], v[80:83], v[168:171], v[112:127]
	ds_read_b128 v[80:83], v215 offset:6784
	v_mfma_f32_32x32x16_bf16 v[112:127], v[84:87], v[172:175], v[112:127]
	ds_read_b128 v[84:87], v215 offset:6816
	v_max3_f32 v10, v96, v97, v98
	v_max3_f32 v10, v10, v99, v100
	v_max3_f32 v10, v10, v101, v102
	v_max3_f32 v10, v10, v103, v104
	v_max3_f32 v10, v10, v105, v106
	v_max3_f32 v10, v10, v107, v108
	v_max3_f32 v10, v10, v109, v110
	v_max_f32_e32 v10, v10, v111
	s_nop 2
	v_max3_f32 v11, v112, v113, v114
	v_max3_f32 v11, v11, v115, v116
	v_max3_f32 v11, v11, v117, v118
	v_max3_f32 v11, v11, v119, v120
	v_max3_f32 v11, v11, v121, v122
	v_max3_f32 v11, v11, v123, v124
	v_max3_f32 v11, v11, v125, v126
	v_max_f32_e32 v11, v11, v127
	v_mov_b32_e32 v12, v10
	v_mov_b32_e32 v13, v11
	s_nop 1
	v_permlane32_swap_b32_e32 v12, v10
	v_permlane32_swap_b32_e32 v13, v11
	v_max_f32_e32 v10, v10, v12
	v_max_f32_e32 v11, v11, v13
	v_max_f32_e32 v0, v10, v11
	v_cmp_lt_f32_e32 vcc, s97, v0
	s_cbranch_vccnz .Lattn_rare_a

; __device__ __forceinline__ unsigned pk2(float lo, float hi) { const f2_t v = {lo, hi}; return __builtin_bit_cast(unsigned, __builtin_convertvector(v, bf2_t)); }
; __device__ void attn_phase(const Params& p, bool last, char* shm, int w0) {
;     ...
;           f32x16 st[2];
; #pragma unroll
;           for (int j = 0; j < 2; ++j)
; #pragma unroll
;             for (int e = 0; e < 16; ++e) st[j][e] = -mrun[j];
;     ...
;             float ls = 0.f;
; #pragma unroll
;             for (int s2 = 0; s2 < 2; ++s2) {
;               const int g0 = s2 * 2; bf16x8 f;
; #pragma unroll
;               for (int j = 0; j < 4; j += 2) {
;                 const float p0 = __builtin_amdgcn_exp2f(st[qt][g0 * 4 + j]), p1 = __builtin_amdgcn_exp2f(st[qt][g0 * 4 + j + 1]);
;                 const float p2 = __builtin_amdgcn_exp2f(st[qt][(g0 + 1) * 4 + j]), p3 = __builtin_amdgcn_exp2f(st[qt][(g0 + 1) * 4 + j + 1]);
;                 ls += (p0 + p1) + (p2 + p3);
;                 const unsigned ww0 = pk2(p0, p1), ww1 = pk2(p2, p3);
;                 f[j] = (short)(ww0 & 0xffffu); f[j + 1] = (short)(ww0 >> 16); f[4 + j] = (short)(ww1 & 0xffffu); f[4 + j + 1] = (short)(ww1 >> 16);
;               }
;               pf[qt][s2] = f;
;             }
;             lrun[qt] += ls;
;           }
; #pragma unroll
;           for (int dt = 0; dt < 2; ++dt)
; #pragma unroll
;             for (int s2 = 0; s2 < 2; ++s2) {
;               const bf16_t* vp = Vb + (dt * 32 + lq) * VSTR + (k2 * 2 + s2) * 16 + hb * 4;
;               const bf16x4 v0 = *(const bf16x4*)vp, v1 = *(const bf16x4*)(vp + 8);
;               bf16x8 vf; vf[0] = v0[0]; vf[1] = v0[1]; vf[2] = v0[2]; vf[3] = v0[3]; vf[4] = v1[0]; vf[5] = v1[1]; vf[6] = v1[2]; vf[7] = v1[3];
;               ot[dt][0] = __builtin_amdgcn_mfma_f32_32x32x16_bf16(vf, pf[0][s2], ot[dt][0], 0, 0, 0);
;               ot[dt][1] = __builtin_amdgcn_mfma_f32_32x32x16_bf16(vf, pf[1][s2], ot[dt][1], 0, 0, 0);
;             }
.Lattn_back_b:
	v_xor_b32_e32 v224, 0x80000000, v217
	v_xor_b32_e32 v225, 0x80000000, v219
	v_exp_f32_e32 v96, v96
	v_exp_f32_e32 v97, v97
	v_exp_f32_e32 v100, v100
	v_exp_f32_e32 v101, v101
	v_exp_f32_e32 v98, v98
	v_exp_f32_e32 v99, v99
	v_exp_f32_e32 v102, v102
	v_exp_f32_e32 v103, v103
	v_add_f32_e32 v0, v97, v96
	v_add_f32_e32 v227, v101, v100
	v_add_f32_e32 v0, v227, v0
	v_add_f32_e32 v227, v99, v98
	v_add_f32_e32 v232, v103, v102
	v_add_f32_e32 v227, v232, v227
	v_add_f32_e32 v192, v227, v0
	v_cvt_pk_bf16_f32 v96, v96, v97
	v_cvt_pk_bf16_f32 v97, v98, v99
	v_cvt_pk_bf16_f32 v98, v100, v101
	v_cvt_pk_bf16_f32 v99, v102, v103
	v_exp_f32_e32 v104, v104
	v_exp_f32_e32 v105, v105
	s_waitcnt lgkmcnt(2)
	v_mfma_f32_32x32x16_bf16 v[48:63], v[88:91], v[96:99], v[48:63]
	v_mfma_f32_32x32x16_bf16 v[64:79], v[242:245], v[96:99], v[64:79]
	v_exp_f32_e32 v108, v108
	v_exp_f32_e32 v109, v109
	v_exp_f32_e32 v106, v106
	v_exp_f32_e32 v107, v107
	v_exp_f32_e32 v110, v110
	v_exp_f32_e32 v111, v111
	v_add_f32_e32 v0, v105, v104
	v_add_f32_e32 v227, v109, v108
	v_add_f32_e32 v0, v227, v0
	v_add_f32_e32 v227, v107, v106
	v_add_f32_e32 v232, v111, v110
	v_add_f32_e32 v227, v232, v227
	v_add_f32_e32 v192, v0, v192
	v_add_f32_e32 v192, v227, v192
	v_cvt_pk_bf16_f32 v104, v104, v105
	v_cvt_pk_bf16_f32 v105, v106, v107
	v_cvt_pk_bf16_f32 v106, v108, v109
	v_cvt_pk_bf16_f32 v107, v110, v111
	v_add_f32_e32 v213, v213, v192
	v_exp_f32_e32 v112, v112
	v_exp_f32_e32 v113, v113
	s_waitcnt lgkmcnt(0)
	v_mfma_f32_32x32x16_bf16 v[48:63], v[92:95], v[104:107], v[48:63]
	v_mfma_f32_32x32x16_bf16 v[64:79], v[246:249], v[104:107], v[64:79]
	v_exp_f32_e32 v116, v116
	v_exp_f32_e32 v117, v117
	v_exp_f32_e32 v114, v114
	v_exp_f32_e32 v115, v115
	v_exp_f32_e32 v118, v118
	v_exp_f32_e32 v119, v119
	v_add_f32_e32 v0, v113, v112
	v_add_f32_e32 v227, v117, v116
	v_add_f32_e32 v0, v227, v0
	v_add_f32_e32 v227, v115, v114
	v_add_f32_e32 v232, v119, v118
	v_add_f32_e32 v227, v232, v227
	v_add_f32_e32 v193, v227, v0
	v_cvt_pk_bf16_f32 v112, v112, v113
	v_cvt_pk_bf16_f32 v113, v114, v115
	v_cvt_pk_bf16_f32 v114, v116, v117
	v_cvt_pk_bf16_f32 v115, v118, v119
	v_mov_b32_e32 v100, v224
	v_mov_b32_e32 v101, v224
	v_mov_b32_e32 v102, v224
	v_mov_b32_e32 v103, v224
	v_mov_b32_e32 v108, v224
	v_mov_b32_e32 v109, v224
	v_mov_b32_e32 v110, v224
	v_mov_b32_e32 v111, v224
	v_exp_f32_e32 v120, v120
	v_exp_f32_e32 v121, v121
	v_mfma_f32_32x32x16_bf16 v[16:31], v[88:91], v[112:115], v[16:31]
	v_mfma_f32_32x32x16_bf16 v[32:47], v[242:245], v[112:115], v[32:47]
	v_exp_f32_e32 v124, v124
	v_exp_f32_e32 v125, v125
	v_exp_f32_e32 v122, v122
	v_exp_f32_e32 v123, v123
	v_exp_f32_e32 v126, v126
	v_exp_f32_e32 v127, v127
	v_add_f32_e32 v0, v121, v120
	v_add_f32_e32 v227, v125, v124
	v_add_f32_e32 v0, v227, v0
	v_add_f32_e32 v227, v123, v122
	v_add_f32_e32 v232, v127, v126
	v_add_f32_e32 v227, v232, v227
	v_add_f32_e32 v193, v0, v193
	v_add_f32_e32 v193, v227, v193
	v_cvt_pk_bf16_f32 v120, v120, v121
	v_cvt_pk_bf16_f32 v121, v122, v123
	v_cvt_pk_bf16_f32 v122, v124, v125
	v_cvt_pk_bf16_f32 v123, v126, v127
	v_add_f32_e32 v216, v216, v193
	v_mov_b32_e32 v96, v224
	v_mov_b32_e32 v97, v224
	v_mov_b32_e32 v98, v224
	v_mov_b32_e32 v99, v224
	v_mov_b32_e32 v104, v224
	v_mov_b32_e32 v105, v224
	v_mov_b32_e32 v106, v224
	v_mov_b32_e32 v107, v224
	v_mfma_f32_32x32x16_bf16 v[16:31], v[92:95], v[120:123], v[16:31]
	v_mfma_f32_32x32x16_bf16 v[32:47], v[246:249], v[120:123], v[32:47]
	v_mov_b32_e32 v116, v225
	v_mov_b32_e32 v117, v225
	v_mov_b32_e32 v118, v225
	v_mov_b32_e32 v119, v225
	v_mov_b32_e32 v124, v225
	v_mov_b32_e32 v125, v225
	v_mov_b32_e32 v126, v225
	v_mov_b32_e32 v127, v225
	v_mov_b32_e32 v112, v225
	v_mov_b32_e32 v113, v225
	v_mov_b32_e32 v114, v225
	v_mov_b32_e32 v115, v225
	v_mov_b32_e32 v120, v225
	v_mov_b32_e32 v121, v225
	v_mov_b32_e32 v122, v225
	v_mov_b32_e32 v123, v225
	s_branch .Lattn_body_end
